# grid barrier master path: acquire before the top generation bump, per-XCD generation bump and its ack wait removed
# baseline (speedup 1.0000x reference)
; __device__ __forceinline__ unsigned xb_ld(unsigned* p)              { return __hip_atomic_load(p, __ATOMIC_RELAXED, __HIP_MEMORY_SCOPE_AGENT); }
; __device__ __forceinline__ unsigned xb_add(unsigned* p, unsigned v) { return __hip_atomic_fetch_add(p, v, __ATOMIC_RELAXED, __HIP_MEMORY_SCOPE_AGENT); }
; #define XB_SPIN(cond, bar) do { unsigned _sp = 0; while (cond) { __builtin_amdgcn_s_sleep(1); \
;     if ((++_sp & 255u) == 0u) { if (xb_ld(&(bar)[XB_TMO])) break; if (_sp > XB_SPIN_CAP) { atomicAdd(&(bar)[XB_TMO], 1u); break; } } } } while (0)
; __device__ __forceinline__ void grid_barrier(const XcdBarrier& b) {
;     ...
;         const unsigned old = xb_add(&bar[XB_XSUB(b.x)], 1u);
;         const unsigned gen = old / nloc;
;         if (old + 1u == (gen + 1u) * nloc) {
;             __builtin_amdgcn_fence(__ATOMIC_RELEASE, "agent");
;             asm volatile("s_waitcnt vmcnt(0)" ::: "memory");
;             const unsigned og = xb_add(&bar[XB_TOP], 1u);
;             const unsigned tg = og / nx;
;             if (og + 1u == (tg + 1u) * nx) xb_add(&bar[XB_TOPGEN], 1u);
;             else XB_SPIN(xb_ld(&bar[XB_TOPGEN]) == tg, bar);
;             __builtin_amdgcn_fence(__ATOMIC_ACQUIRE, "agent");
;             xb_add(&bar[XB_XGEN(b.x)], 1u);
;             asm volatile("s_waitcnt vmcnt(0)" ::: "memory");
.LBB0_159:
	s_or_b64 exec, exec, s[12:13]
.LBB0_160:
	s_or_b64 exec, exec, s[0:1]
	s_add_i32 s31, s31, 1
	s_cmp_eq_u32 s31, 4
	s_waitcnt lgkmcnt(0)
	s_barrier
	s_cbranch_scc1 .LBB0_907

; __device__ __forceinline__ unsigned xb_ld(unsigned* p)              { return __hip_atomic_load(p, __ATOMIC_RELAXED, __HIP_MEMORY_SCOPE_AGENT); }
; __device__ __forceinline__ unsigned xb_add(unsigned* p, unsigned v) { return __hip_atomic_fetch_add(p, v, __ATOMIC_RELAXED, __HIP_MEMORY_SCOPE_AGENT); }
; #define XB_SPIN(cond, bar) do { unsigned _sp = 0; while (cond) { __builtin_amdgcn_s_sleep(1); \
;     if ((++_sp & 255u) == 0u) { if (xb_ld(&(bar)[XB_TMO])) break; if (_sp > XB_SPIN_CAP) { atomicAdd(&(bar)[XB_TMO], 1u); break; } } } } while (0)
; __device__ __forceinline__ void grid_barrier(const XcdBarrier& b) {
;     ...
;         const unsigned old = xb_add(&bar[XB_XSUB(b.x)], 1u);
;         const unsigned gen = old / nloc;
;         if (old + 1u == (gen + 1u) * nloc) {
;             __builtin_amdgcn_fence(__ATOMIC_RELEASE, "agent");
;             asm volatile("s_waitcnt vmcnt(0)" ::: "memory");
;             const unsigned og = xb_add(&bar[XB_TOP], 1u);
;             const unsigned tg = og / nx;
;             if (og + 1u == (tg + 1u) * nx) xb_add(&bar[XB_TOPGEN], 1u);
;             else XB_SPIN(xb_ld(&bar[XB_TOPGEN]) == tg, bar);
;             __builtin_amdgcn_fence(__ATOMIC_ACQUIRE, "agent");
;             xb_add(&bar[XB_XGEN(b.x)], 1u);
;             asm volatile("s_waitcnt vmcnt(0)" ::: "memory");
.LBB0_348:
	s_or_b64 exec, exec, s[12:13]
	buffer_inv sc1
	s_waitcnt vmcnt(0)
	s_and_saveexec_b64 s[12:13], s[14:15]
	s_cbranch_execz .LBB0_350
	global_atomic_add v[2:3], v204, off
.LBB0_350:
	s_or_b64 exec, exec, s[12:13]
.LBB0_351:
	s_or_b64 exec, exec, s[0:1]
	s_waitcnt lgkmcnt(0)
	s_barrier
	s_mov_b64 s[0:1], -1
	s_branch .LBB0_353

; __device__ __forceinline__ unsigned xb_ld(unsigned* p)              { return __hip_atomic_load(p, __ATOMIC_RELAXED, __HIP_MEMORY_SCOPE_AGENT); }
; __device__ __forceinline__ unsigned xb_add(unsigned* p, unsigned v) { return __hip_atomic_fetch_add(p, v, __ATOMIC_RELAXED, __HIP_MEMORY_SCOPE_AGENT); }
; #define XB_SPIN(cond, bar) do { unsigned _sp = 0; while (cond) { __builtin_amdgcn_s_sleep(1); \
;     if ((++_sp & 255u) == 0u) { if (xb_ld(&(bar)[XB_TMO])) break; if (_sp > XB_SPIN_CAP) { atomicAdd(&(bar)[XB_TMO], 1u); break; } } } } while (0)
; __device__ __forceinline__ void grid_barrier(const XcdBarrier& b) {
;     ...
;         const unsigned old = xb_add(&bar[XB_XSUB(b.x)], 1u);
;         const unsigned gen = old / nloc;
;         if (old + 1u == (gen + 1u) * nloc) {
;             __builtin_amdgcn_fence(__ATOMIC_RELEASE, "agent");
;             asm volatile("s_waitcnt vmcnt(0)" ::: "memory");
;             const unsigned og = xb_add(&bar[XB_TOP], 1u);
;             const unsigned tg = og / nx;
;             if (og + 1u == (tg + 1u) * nx) xb_add(&bar[XB_TOPGEN], 1u);
;             else XB_SPIN(xb_ld(&bar[XB_TOPGEN]) == tg, bar);
;             __builtin_amdgcn_fence(__ATOMIC_ACQUIRE, "agent");
;             xb_add(&bar[XB_XGEN(b.x)], 1u);
;             asm volatile("s_waitcnt vmcnt(0)" ::: "memory");
.LBB0_586:
	s_or_b64 exec, exec, s[12:13]
.LBB0_587:
	s_or_b64 exec, exec, s[0:1]
	s_lshl_b32 s76, s31, 3
	s_lshl_b64 s[0:1], s[76:77], 2
	s_add_u32 s0, s58, s0
	s_addc_u32 s1, s59, s1
	s_add_u32 s12, s0, 0x2d834708
	s_addc_u32 s13, s1, 0
	s_mov_b64 s[0:1], -1
	s_waitcnt lgkmcnt(0)
	s_barrier
	s_branch .LBB0_590
.LBB0_588:
	s_or_b64 exec, exec, s[16:17]
.LBB0_589:
	s_or_b64 exec, exec, s[0:1]
	s_mov_b64 s[0:1], 0
	s_and_b64 vcc, exec, s[14:15]
	s_waitcnt lgkmcnt(0)
	s_barrier
	s_cbranch_vccnz .LBB0_832

; __device__ __forceinline__ unsigned xb_ld(unsigned* p)              { return __hip_atomic_load(p, __ATOMIC_RELAXED, __HIP_MEMORY_SCOPE_AGENT); }
; __device__ __forceinline__ unsigned xb_add(unsigned* p, unsigned v) { return __hip_atomic_fetch_add(p, v, __ATOMIC_RELAXED, __HIP_MEMORY_SCOPE_AGENT); }
; #define XB_SPIN(cond, bar) do { unsigned _sp = 0; while (cond) { __builtin_amdgcn_s_sleep(1); \
;     if ((++_sp & 255u) == 0u) { if (xb_ld(&(bar)[XB_TMO])) break; if (_sp > XB_SPIN_CAP) { atomicAdd(&(bar)[XB_TMO], 1u); break; } } } } while (0)
; __device__ __forceinline__ void grid_barrier(const XcdBarrier& b) {
;     ...
;         const unsigned old = xb_add(&bar[XB_XSUB(b.x)], 1u);
;         const unsigned gen = old / nloc;
;         if (old + 1u == (gen + 1u) * nloc) {
;             __builtin_amdgcn_fence(__ATOMIC_RELEASE, "agent");
;             asm volatile("s_waitcnt vmcnt(0)" ::: "memory");
;             const unsigned og = xb_add(&bar[XB_TOP], 1u);
;             const unsigned tg = og / nx;
;             if (og + 1u == (tg + 1u) * nx) xb_add(&bar[XB_TOPGEN], 1u);
;             else XB_SPIN(xb_ld(&bar[XB_TOPGEN]) == tg, bar);
;             __builtin_amdgcn_fence(__ATOMIC_ACQUIRE, "agent");
;             xb_add(&bar[XB_XGEN(b.x)], 1u);
;             asm volatile("s_waitcnt vmcnt(0)" ::: "memory");
.LBB0_830:
	s_or_b64 exec, exec, s[16:17]
	buffer_inv sc1
	s_waitcnt vmcnt(0)
	s_and_saveexec_b64 s[16:17], s[18:19]
	s_cbranch_execz .LBB0_588
	global_atomic_add v[2:3], v204, off
	s_branch .LBB0_588

; __device__ __forceinline__ unsigned xb_ld(unsigned* p)              { return __hip_atomic_load(p, __ATOMIC_RELAXED, __HIP_MEMORY_SCOPE_AGENT); }
; __device__ __forceinline__ unsigned xb_add(unsigned* p, unsigned v) { return __hip_atomic_fetch_add(p, v, __ATOMIC_RELAXED, __HIP_MEMORY_SCOPE_AGENT); }
; #define XB_SPIN(cond, bar) do { unsigned _sp = 0; while (cond) { __builtin_amdgcn_s_sleep(1); \
;     if ((++_sp & 255u) == 0u) { if (xb_ld(&(bar)[XB_TMO])) break; if (_sp > XB_SPIN_CAP) { atomicAdd(&(bar)[XB_TMO], 1u); break; } } } } while (0)
; __device__ __forceinline__ void grid_barrier(const XcdBarrier& b) {
;     ...
;         const unsigned old = xb_add(&bar[XB_XSUB(b.x)], 1u);
;         const unsigned gen = old / nloc;
;         if (old + 1u == (gen + 1u) * nloc) {
;             __builtin_amdgcn_fence(__ATOMIC_RELEASE, "agent");
;             asm volatile("s_waitcnt vmcnt(0)" ::: "memory");
;             const unsigned og = xb_add(&bar[XB_TOP], 1u);
;             const unsigned tg = og / nx;
;             if (og + 1u == (tg + 1u) * nx) xb_add(&bar[XB_TOPGEN], 1u);
;             else XB_SPIN(xb_ld(&bar[XB_TOPGEN]) == tg, bar);
;             __builtin_amdgcn_fence(__ATOMIC_ACQUIRE, "agent");
;             xb_add(&bar[XB_XGEN(b.x)], 1u);
;             asm volatile("s_waitcnt vmcnt(0)" ::: "memory");
.LBB0_905:
	s_or_b64 exec, exec, s[12:13]
	buffer_inv sc1
	s_waitcnt vmcnt(0)
	s_and_saveexec_b64 s[12:13], s[14:15]
	s_cbranch_execz .LBB0_159
	global_atomic_add v[2:3], v204, off
	s_branch .LBB0_159
